# down GEMM epilogue: row slots, row gates, bias and expert count prefetched per tile by LDS-DMA at the tile head (double-buffered in the LDS area only the gate/up phase uses) and read with ds_read, ins
# baseline (speedup 1.0000x reference)
; template <bool GATHER, bool FP8, class Epi, class Sched>
; __device__ __forceinline__ void gemm_phase(LAS unsigned char* lds, const int tid, const int K, const Sched& S, const Epi& E) {
;     ...
;         const bool has_next = S.next(ui + 1, nxt);
;         if constexpr (Epi::LDSBIAS) { if (wid == 0) E.stage_bias(lds + BIAS_OFF + (ui & 1) * 1024, cur); }
;         const char* nA = has_next ? S.aptr(nxt) : cA; const char* nB = has_next ? S.bptr(nxt) : cB;
; #pragma unroll 1
;         for (int t = 0; t < nt; t += 2) {
;             const bool last = (t == nt - 2);
;             if (GATHER && last && has_next) { PG8_LOADOFF(o2, ui + 1); }
;             const char* a1 = cA + (size_t)(t + 1) * kstep;
;             const char* a2 = last ? nA : cA + (size_t)(t + 2) * kstep; const char* b2 = last ? nB : cB + (size_t)(t + 2) * kstepB;
;             const char* a3 = a2 + kstep; const char* b3 = b2 + kstepB;
;             PG8_LDB(B0, 0, 0); PG8_LDB(B1, 0, 1); PG8_SCHED; PG8_LDA(At, 0, 0); PG8_STAGE(PG8_SA(1, 1), a1 + hsA, oC[1]);
;             PG8_WAIT_V(8); PG8_WAIT_L(0); PG8_BAR; PG8_MMA(0, 0, At, B0); PG8_MMA(0, 1, At, B1); PG8_BAR; PG8_SCHED;
;             PG8_LDA(At, 0, 1); PG8_STAGE(PG8_SB(0, 0), b2, voffB); PG8_STAGE(PG8_SB(0, 1), b2 + hstepB, voffB); PG8_STAGE(PG8_SA(0, 0), a2, o2[0]);
;             PG8_WAIT_V(8); PG8_WAIT_L(0); PG8_BAR; PG8_MMA(1, 0, At, B0); PG8_MMA(1, 1, At, B1); PG8_BAR; PG8_SCHED;
;             PG8_LDB(B0, 1, 0); PG8_LDB(B1, 1, 1); PG8_SCHED; PG8_LDA(At, 1, 0); PG8_STAGE(PG8_SA(0, 1), a2 + hsA, o2[1]);
;             PG8_WAIT_V(8); PG8_WAIT_L(0); PG8_BAR; PG8_MMA(0, 0, At, B0); PG8_MMA(0, 1, At, B1); PG8_BAR; PG8_SCHED;
;             PG8_LDA(At, 1, 1); PG8_STAGE(PG8_SB(1, 0), b3, voffB); PG8_STAGE(PG8_SB(1, 1), b3 + hstepB, voffB); PG8_STAGE(PG8_SA(1, 0), a3, o2[0]);
;             PG8_WAIT_V(8); PG8_WAIT_L(0); PG8_BAR; PG8_MMA(1, 0, At, B0); PG8_MMA(1, 1, At, B1); PG8_BAR; PG8_SCHED;
;         }
;         if (wr == 0) PG8_BAR;
;         { int t2 = tid; asm volatile("" : "+v"(t2)); const int l2 = t2 & 63; E(acc, cur, wr, wc, l2 & 15, l2 >> 4, (const LAS float*)(lds + BIAS_OFF + (ui & 1) * 1024)); }
;         if (!has_next) break;
; #pragma unroll
;         for (int a = 0; a < 2; ++a)
; #pragma unroll
;             for (int b = 0; b < 2; ++b)
; #pragma unroll
;                 for (int m = 0; m < 4; ++m)
; #pragma unroll
.LBB0_41:
	s_ashr_i32 s51, s50, 31
	s_lshl_b64 s[26:27], s[50:51], 18
	v_readlane_b32 s0, v251, 21
	v_readlane_b32 s1, v251, 22
	s_add_u32 s52, s0, s26
	s_addc_u32 s53, s1, s27
	s_and_b64 s[26:27], s[44:45], exec
	s_cselect_b32 s12, s53, s21
	s_cselect_b32 s17, s52, s20
	s_ashr_i32 s47, s46, 31
	s_lshl_b64 s[26:27], s[46:47], 20
	v_readlane_b32 s0, v254, 51
	s_add_u32 s0, s0, s26
	v_readlane_b32 s1, v254, 52
	s_addc_u32 s1, s1, s27
	s_ashr_i32 s39, s38, 31
	s_lshl_b64 s[26:27], s[38:39], 18
	s_add_u32 s54, s0, s26
	s_addc_u32 s55, s1, s27
	s_and_b64 s[26:27], s[44:45], exec
	s_cselect_b32 s39, s55, s23
	s_cselect_b32 s47, s54, s22
	s_add_u32 s51, s22, 0x10000
	s_addc_u32 s57, s23, 0
	s_add_u32 s20, s20, 0x20080
	s_addc_u32 s21, s21, 0
	s_mov_b32 vcc_lo, -2
	v_mov_b64_e32 v[34:35], 0
	v_mov_b64_e32 v[36:37], 0
	v_mov_b64_e32 v[40:41], 0
	v_mov_b64_e32 v[42:43], 0
	v_mov_b64_e32 v[52:53], 0
	v_mov_b64_e32 v[54:55], 0
	v_mov_b64_e32 v[56:57], 0
	v_mov_b64_e32 v[58:59], 0
	v_mov_b64_e32 v[68:69], 0
	v_mov_b64_e32 v[70:71], 0
	v_mov_b64_e32 v[72:73], 0
	v_mov_b64_e32 v[74:75], 0
	v_mov_b64_e32 v[84:85], 0
	v_mov_b64_e32 v[86:87], 0
	v_mov_b64_e32 v[88:89], 0
	v_mov_b64_e32 v[90:91], 0
	v_mov_b64_e32 v[44:45], 0
	v_mov_b64_e32 v[46:47], 0
	v_mov_b64_e32 v[48:49], 0
	v_mov_b64_e32 v[50:51], 0
	v_mov_b64_e32 v[60:61], 0
	v_mov_b64_e32 v[62:63], 0
	v_mov_b64_e32 v[64:65], 0
	v_mov_b64_e32 v[66:67], 0
	v_mov_b64_e32 v[76:77], 0
	v_mov_b64_e32 v[78:79], 0
	v_mov_b64_e32 v[80:81], 0
	v_mov_b64_e32 v[82:83], 0
	v_mov_b64_e32 v[92:93], 0
	v_mov_b64_e32 v[94:95], 0
	v_mov_b64_e32 v[96:97], 0
	v_mov_b64_e32 v[98:99], 0
	v_mov_b64_e32 v[100:101], 0
	v_mov_b64_e32 v[102:103], 0
	v_mov_b64_e32 v[104:105], 0
	v_mov_b64_e32 v[106:107], 0
	v_mov_b64_e32 v[116:117], 0
	v_mov_b64_e32 v[118:119], 0
	v_mov_b64_e32 v[120:121], 0
	v_mov_b64_e32 v[122:123], 0
	v_mov_b64_e32 v[132:133], 0
	v_mov_b64_e32 v[134:135], 0
	v_mov_b64_e32 v[136:137], 0
	v_mov_b64_e32 v[138:139], 0
	v_mov_b64_e32 v[148:149], 0
	v_mov_b64_e32 v[150:151], 0
	v_mov_b64_e32 v[152:153], 0
	v_mov_b64_e32 v[154:155], 0
	v_mov_b64_e32 v[108:109], 0
	v_mov_b64_e32 v[110:111], 0
	v_mov_b64_e32 v[112:113], 0
	v_mov_b64_e32 v[114:115], 0
	v_mov_b64_e32 v[124:125], 0
	v_mov_b64_e32 v[126:127], 0
	v_mov_b64_e32 v[128:129], 0
	v_mov_b64_e32 v[130:131], 0
	v_mov_b64_e32 v[140:141], 0
	v_mov_b64_e32 v[142:143], 0
	v_mov_b64_e32 v[144:145], 0
	v_mov_b64_e32 v[146:147], 0
	v_mov_b64_e32 v[156:157], 0
	v_mov_b64_e32 v[158:159], 0
	v_mov_b64_e32 v[160:161], 0
	v_mov_b64_e32 v[162:163], 0
	v_readlane_b32 s98, v249, 52
	s_and_b32 s101, s16, 1
	s_lshl_b32 s101, s101, 12
	s_cmp_lg_u32 s98, 0
	s_cbranch_scc1 .Ldn_dma_skip
	v_lshlrev_b32_e32 v0, 4, v248
	v_readlane_b32 s98, v251, 25
	v_readlane_b32 s99, v251, 26
	s_lshl_b32 s100, s40, 10
	v_add_u32_e32 v2, s100, v0
	v_mov_b32_e32 v3, 0
	s_add_i32 m0, s101, 0x20100
	v_lshl_add_u64 v[2:3], s[98:99], 0, v[2:3]
	global_load_lds_dwordx4 v[2:3], off
	v_readlane_b32 s98, v251, 27
	v_readlane_b32 s99, v251, 28
	v_add_u32_e32 v4, s100, v0
	v_mov_b32_e32 v5, 0
	s_add_i32 m0, s101, 0x20500
	v_lshl_add_u64 v[4:5], s[98:99], 0, v[4:5]
	global_load_lds_dwordx4 v[4:5], off
	v_readlane_b32 s98, v254, 53
	v_readlane_b32 s99, v254, 54
	s_lshl_b32 s100, s56, 12
	v_add_u32_e32 v6, s100, v0
	s_lshl_b32 s100, s58, 10
	v_add_u32_e32 v6, s100, v6
	v_mov_b32_e32 v7, 0
	s_add_i32 m0, s101, 0x20900
	v_lshl_add_u64 v[6:7], s[98:99], 0, v[6:7]
	global_load_lds_dwordx4 v[6:7], off
	v_readlane_b32 s98, v254, 49
	v_readlane_b32 s99, v254, 50
	v_lshlrev_b32_e32 v8, 2, v248
	v_mov_b32_e32 v9, 0
	s_add_i32 m0, s101, 0x20d00
	v_lshl_add_u64 v[8:9], s[98:99], 0, v[8:9]
	global_load_lds_dword v[8:9], off
.Ldn_dma_skip:
.LBB0_42:
	ds_read_b128 v[16:19], v212
	ds_read_b128 v[20:23], v213
	ds_read_b128 v[24:27], v214
	ds_read_b128 v[28:31], v215
	ds_read_b128 v[0:3], v216
	ds_read_b128 v[4:7], v217
	ds_read_b128 v[8:11], v218
	ds_read_b128 v[12:15], v219
	s_add_u32 s0, s20, 0xfffe0080
	s_addc_u32 s1, s21, -1
	s_cmp_eq_u32 vcc_lo, 4
	s_cselect_b32 s27, s12, s1
	s_cselect_b32 s26, s17, s0
	s_cselect_b32 s23, s39, s57
	s_cselect_b32 s22, s47, s51
	v_lshl_add_u64 v[164:165], s[20:21], 0, v[178:179]
	s_add_i32 m0, s41, 0xc000
	ds_read_b128 v[194:197], v228
	ds_read_b128 v[198:201], v228 offset:1024
	ds_read_b128 v[230:233], v228 offset:2048
	ds_read_b128 v[234:237], v228 offset:3072
	ds_read_b128 v[238:241], v228 offset:4096
	ds_read_b128 v[242:245], v228 offset:5120
	ds_read_b128 v[182:185], v228 offset:6144
	ds_read_b128 v[186:189], v228 offset:7168
	global_load_lds_dwordx4 v[164:165], off
	v_lshl_add_u64 v[164:165], s[20:21], 0, v[180:181]
	s_add_i32 m0, s41, 0xe000
	s_nop 0
	global_load_lds_dwordx4 v[164:165], off
	s_waitcnt vmcnt(8)
	s_waitcnt lgkmcnt(0)
	s_barrier
; #define PG8_STAGE(bufoff, gbase, voff) do { _Pragma("unroll") for (int _i = 0; _i < 2; ++_i) \
;         __builtin_amdgcn_global_load_lds((const unsigned*)((const char*)(gbase) + (voff)[_i]), (LAS unsigned*)(lds + (bufoff) + ldsw + _i * 8192), 16, 0, 0); } while (0)
; #define PG8_WAIT_V(n) asm volatile("s_waitcnt vmcnt(" #n ")" ::: "memory")
; #define PG8_WAIT_L(n) asm volatile("s_waitcnt lgkmcnt(" #n ")" ::: "memory")
; #define PG8_BAR __builtin_amdgcn_s_barrier()
; #define PG8_SCHED __builtin_amdgcn_sched_barrier(0)
; template <bool GATHER, bool FP8, class Epi, class Sched>
; __device__ __forceinline__ void gemm_phase(LAS unsigned char* lds, const int tid, const int K, const Sched& S, const Epi& E) {
;     ...
;             PG8_LDB(B0, 0, 0); PG8_LDB(B1, 0, 1); PG8_SCHED; PG8_LDA(At, 0, 0); PG8_STAGE(PG8_SA(1, 1), a1 + hsA, oC[1]);
;             PG8_WAIT_V(8); PG8_WAIT_L(0); PG8_BAR; PG8_MMA(0, 0, At, B0); PG8_MMA(0, 1, At, B1); PG8_BAR; PG8_SCHED;
;             PG8_LDA(At, 0, 1); PG8_STAGE(PG8_SB(0, 0), b2, voffB); PG8_STAGE(PG8_SB(0, 1), b2 + hstepB, voffB); PG8_STAGE(PG8_SA(0, 0), a2, o2[0]);
;             PG8_WAIT_V(8); PG8_WAIT_L(0); PG8_BAR; PG8_MMA(1, 0, At, B0); PG8_MMA(1, 1, At, B1); PG8_BAR; PG8_SCHED;
;             PG8_LDB(B0, 1, 0); PG8_LDB(B1, 1, 1); PG8_SCHED; PG8_LDA(At, 1, 0); PG8_STAGE(PG8_SA(0, 1), a2 + hsA, o2[1]);
;             PG8_WAIT_V(8); PG8_WAIT_L(0); PG8_BAR; PG8_MMA(0, 0, At, B0); PG8_MMA(0, 1, At, B1); PG8_BAR; PG8_SCHED;
	s_setprio 1
	s_waitcnt lgkmcnt(0)
	v_mfma_scale_f32_16x16x128_f8f6f4 v[160:163], v[16:23], v[194:201], v[160:163], v39, v39 op_sel_hi:[0,0,0]
	v_mfma_scale_f32_16x16x128_f8f6f4 v[156:159], v[24:31], v[194:201], v[156:159], v39, v39 op_sel_hi:[0,0,0]
	v_mfma_scale_f32_16x16x128_f8f6f4 v[144:147], v[16:23], v[230:237], v[144:147], v39, v39 op_sel_hi:[0,0,0]
	v_mfma_scale_f32_16x16x128_f8f6f4 v[140:143], v[24:31], v[230:237], v[140:143], v39, v39 op_sel_hi:[0,0,0]
	v_mfma_scale_f32_16x16x128_f8f6f4 v[128:131], v[16:23], v[238:245], v[128:131], v39, v39 op_sel_hi:[0,0,0]
	v_mfma_scale_f32_16x16x128_f8f6f4 v[124:127], v[24:31], v[238:245], v[124:127], v39, v39 op_sel_hi:[0,0,0]
	v_mfma_scale_f32_16x16x128_f8f6f4 v[112:115], v[16:23], v[182:189], v[112:115], v39, v39 op_sel_hi:[0,0,0]
	v_mfma_scale_f32_16x16x128_f8f6f4 v[108:111], v[24:31], v[182:189], v[108:111], v39, v39 op_sel_hi:[0,0,0]
	s_setprio 0
	s_setprio 1
	v_mfma_scale_f32_16x16x128_f8f6f4 v[152:155], v[0:7], v[194:201], v[152:155], v39, v39 op_sel_hi:[0,0,0]
	v_mfma_scale_f32_16x16x128_f8f6f4 v[148:151], v[8:15], v[194:201], v[148:151], v39, v39 op_sel_hi:[0,0,0]
	v_mfma_scale_f32_16x16x128_f8f6f4 v[136:139], v[0:7], v[230:237], v[136:139], v39, v39 op_sel_hi:[0,0,0]
	v_mfma_scale_f32_16x16x128_f8f6f4 v[132:135], v[8:15], v[230:237], v[132:135], v39, v39 op_sel_hi:[0,0,0]
	v_mfma_scale_f32_16x16x128_f8f6f4 v[120:123], v[0:7], v[238:245], v[120:123], v39, v39 op_sel_hi:[0,0,0]
	v_mfma_scale_f32_16x16x128_f8f6f4 v[116:119], v[8:15], v[238:245], v[116:119], v39, v39 op_sel_hi:[0,0,0]
	v_mfma_scale_f32_16x16x128_f8f6f4 v[104:107], v[0:7], v[182:189], v[104:107], v39, v39 op_sel_hi:[0,0,0]
	v_mfma_scale_f32_16x16x128_f8f6f4 v[100:103], v[8:15], v[182:189], v[100:103], v39, v39 op_sel_hi:[0,0,0]
	s_setprio 0
	s_barrier
	s_mov_b32 m0, s59
	v_lshl_add_u64 v[164:165], s[22:23], 0, v[174:175]
	s_add_u32 s0, s22, 0x4000
	ds_read_b128 v[194:197], v228 offset:16384
	ds_read_b128 v[198:201], v228 offset:17408
	ds_read_b128 v[230:233], v228 offset:18432
	ds_read_b128 v[234:237], v228 offset:19456
	ds_read_b128 v[238:241], v228 offset:20480
	ds_read_b128 v[242:245], v228 offset:21504
	ds_read_b128 v[186:189], v228 offset:22528
	ds_read_b128 v[190:193], v228 offset:23552
	global_load_lds_dwordx4 v[164:165], off
	v_lshl_add_u64 v[164:165], s[22:23], 0, v[176:177]
	s_mov_b32 m0, s60
	s_addc_u32 s1, s23, 0
	global_load_lds_dwordx4 v[164:165], off
	v_lshl_add_u64 v[164:165], s[0:1], 0, v[174:175]
	s_mov_b32 m0, s61
	v_lshl_add_u64 v[182:183], s[26:27], 0, v[32:33]
	global_load_lds_dwordx4 v[164:165], off
	v_lshl_add_u64 v[164:165], s[0:1], 0, v[176:177]
	s_mov_b32 m0, s62
	v_lshl_add_u64 v[184:185], s[26:27], 0, v[172:173]
	global_load_lds_dwordx4 v[164:165], off
	s_mov_b32 m0, s41
	s_nop 0
	global_load_lds_dwordx4 v[182:183], off
	s_mov_b32 m0, s63
	s_nop 0
	global_load_lds_dwordx4 v[184:185], off
	s_waitcnt vmcnt(8)
	s_waitcnt lgkmcnt(0)
	s_barrier
	s_setprio 1
	s_waitcnt lgkmcnt(0)
	v_mfma_scale_f32_16x16x128_f8f6f4 v[96:99], v[16:23], v[194:201], v[96:99], v39, v39 op_sel_hi:[0,0,0]
	v_mfma_scale_f32_16x16x128_f8f6f4 v[92:95], v[24:31], v[194:201], v[92:95], v39, v39 op_sel_hi:[0,0,0]
	v_mfma_scale_f32_16x16x128_f8f6f4 v[80:83], v[16:23], v[230:237], v[80:83], v39, v39 op_sel_hi:[0,0,0]
	v_mfma_scale_f32_16x16x128_f8f6f4 v[76:79], v[24:31], v[230:237], v[76:79], v39, v39 op_sel_hi:[0,0,0]
	v_mfma_scale_f32_16x16x128_f8f6f4 v[64:67], v[16:23], v[238:245], v[64:67], v39, v39 op_sel_hi:[0,0,0]
	v_mfma_scale_f32_16x16x128_f8f6f4 v[60:63], v[24:31], v[238:245], v[60:63], v39, v39 op_sel_hi:[0,0,0]
	v_mfma_scale_f32_16x16x128_f8f6f4 v[48:51], v[16:23], v[186:193], v[48:51], v39, v39 op_sel_hi:[0,0,0]
	v_mfma_scale_f32_16x16x128_f8f6f4 v[44:47], v[24:31], v[186:193], v[44:47], v39, v39 op_sel_hi:[0,0,0]
	s_setprio 0
	s_setprio 1
	v_mfma_scale_f32_16x16x128_f8f6f4 v[88:91], v[0:7], v[194:201], v[88:91], v39, v39 op_sel_hi:[0,0,0]
	v_mfma_scale_f32_16x16x128_f8f6f4 v[84:87], v[8:15], v[194:201], v[84:87], v39, v39 op_sel_hi:[0,0,0]
	v_mfma_scale_f32_16x16x128_f8f6f4 v[72:75], v[0:7], v[230:237], v[72:75], v39, v39 op_sel_hi:[0,0,0]
	v_mfma_scale_f32_16x16x128_f8f6f4 v[68:71], v[8:15], v[230:237], v[68:71], v39, v39 op_sel_hi:[0,0,0]
	v_mfma_scale_f32_16x16x128_f8f6f4 v[56:59], v[0:7], v[238:245], v[56:59], v39, v39 op_sel_hi:[0,0,0]
	v_mfma_scale_f32_16x16x128_f8f6f4 v[52:55], v[8:15], v[238:245], v[52:55], v39, v39 op_sel_hi:[0,0,0]
	v_mfma_scale_f32_16x16x128_f8f6f4 v[40:43], v[0:7], v[186:193], v[40:43], v39, v39 op_sel_hi:[0,0,0]
	v_mfma_scale_f32_16x16x128_f8f6f4 v[34:37], v[8:15], v[186:193], v[34:37], v39, v39 op_sel_hi:[0,0,0]
	s_setprio 0
	s_barrier
	ds_read_b128 v[0:3], v220
	ds_read_b128 v[4:7], v221
	ds_read_b128 v[8:11], v222
	ds_read_b128 v[12:15], v223
	ds_read_b128 v[16:19], v224
	ds_read_b128 v[20:23], v225
	ds_read_b128 v[24:27], v226
	ds_read_b128 v[28:31], v227
	s_add_u32 s0, s26, 0x20000
	s_addc_u32 s1, s27, 0
	s_mov_b32 m0, s64
	v_lshl_add_u64 v[164:165], s[0:1], 0, v[32:33]
	ds_read_b128 v[186:189], v228 offset:32768
	ds_read_b128 v[190:193], v228 offset:33792
	ds_read_b128 v[194:197], v228 offset:34816
	ds_read_b128 v[198:201], v228 offset:35840
	ds_read_b128 v[230:233], v228 offset:36864
	ds_read_b128 v[234:237], v228 offset:37888
	ds_read_b128 v[238:241], v228 offset:38912
	ds_read_b128 v[242:245], v228 offset:39936
	global_load_lds_dwordx4 v[164:165], off
	v_lshl_add_u64 v[164:165], s[0:1], 0, v[172:173]
	s_mov_b32 m0, s65
	s_nop 0
	global_load_lds_dwordx4 v[164:165], off
	s_waitcnt vmcnt(8)
	s_waitcnt lgkmcnt(0)
	s_barrier
; #define PG8_STAGE(bufoff, gbase, voff) do { _Pragma("unroll") for (int _i = 0; _i < 2; ++_i) \
;         __builtin_amdgcn_global_load_lds((const unsigned*)((const char*)(gbase) + (voff)[_i]), (LAS unsigned*)(lds + (bufoff) + ldsw + _i * 8192), 16, 0, 0); } while (0)
; #define PG8_WAIT_V(n) asm volatile("s_waitcnt vmcnt(" #n ")" ::: "memory")
; #define PG8_WAIT_L(n) asm volatile("s_waitcnt lgkmcnt(" #n ")" ::: "memory")
; #define PG8_BAR __builtin_amdgcn_s_barrier()
; #define PG8_SCHED __builtin_amdgcn_sched_barrier(0)
; template <bool GATHER, bool FP8, class Epi, class Sched>
; __device__ __forceinline__ void gemm_phase(LAS unsigned char* lds, const int tid, const int K, const Sched& S, const Epi& E) {
;     ...
;             PG8_LDB(B0, 1, 0); PG8_LDB(B1, 1, 1); PG8_SCHED; PG8_LDA(At, 1, 0); PG8_STAGE(PG8_SA(0, 1), a2 + hsA, o2[1]);
;             PG8_WAIT_V(8); PG8_WAIT_L(0); PG8_BAR; PG8_MMA(0, 0, At, B0); PG8_MMA(0, 1, At, B1); PG8_BAR; PG8_SCHED;
;             PG8_LDA(At, 1, 1); PG8_STAGE(PG8_SB(1, 0), b3, voffB); PG8_STAGE(PG8_SB(1, 1), b3 + hstepB, voffB); PG8_STAGE(PG8_SA(1, 0), a3, o2[0]);
;             PG8_WAIT_V(8); PG8_WAIT_L(0); PG8_BAR; PG8_MMA(1, 0, At, B0); PG8_MMA(1, 1, At, B1); PG8_BAR; PG8_SCHED;
;         }
;         if (wr == 0) PG8_BAR;
	s_setprio 1
	s_waitcnt lgkmcnt(0)
	v_mfma_scale_f32_16x16x128_f8f6f4 v[160:163], v[0:7], v[186:193], v[160:163], v39, v39 op_sel_hi:[0,0,0]
	v_mfma_scale_f32_16x16x128_f8f6f4 v[156:159], v[8:15], v[186:193], v[156:159], v39, v39 op_sel_hi:[0,0,0]
	v_mfma_scale_f32_16x16x128_f8f6f4 v[144:147], v[0:7], v[194:201], v[144:147], v39, v39 op_sel_hi:[0,0,0]
	v_mfma_scale_f32_16x16x128_f8f6f4 v[140:143], v[8:15], v[194:201], v[140:143], v39, v39 op_sel_hi:[0,0,0]
	v_mfma_scale_f32_16x16x128_f8f6f4 v[128:131], v[0:7], v[230:237], v[128:131], v39, v39 op_sel_hi:[0,0,0]
	v_mfma_scale_f32_16x16x128_f8f6f4 v[124:127], v[8:15], v[230:237], v[124:127], v39, v39 op_sel_hi:[0,0,0]
	v_mfma_scale_f32_16x16x128_f8f6f4 v[112:115], v[0:7], v[238:245], v[112:115], v39, v39 op_sel_hi:[0,0,0]
	v_mfma_scale_f32_16x16x128_f8f6f4 v[108:111], v[8:15], v[238:245], v[108:111], v39, v39 op_sel_hi:[0,0,0]
	s_setprio 0
	s_setprio 1
	v_mfma_scale_f32_16x16x128_f8f6f4 v[152:155], v[16:23], v[186:193], v[152:155], v39, v39 op_sel_hi:[0,0,0]
	v_mfma_scale_f32_16x16x128_f8f6f4 v[148:151], v[24:31], v[186:193], v[148:151], v39, v39 op_sel_hi:[0,0,0]
	v_mfma_scale_f32_16x16x128_f8f6f4 v[136:139], v[16:23], v[194:201], v[136:139], v39, v39 op_sel_hi:[0,0,0]
	v_mfma_scale_f32_16x16x128_f8f6f4 v[132:135], v[24:31], v[194:201], v[132:135], v39, v39 op_sel_hi:[0,0,0]
	v_mfma_scale_f32_16x16x128_f8f6f4 v[120:123], v[16:23], v[230:237], v[120:123], v39, v39 op_sel_hi:[0,0,0]
	v_mfma_scale_f32_16x16x128_f8f6f4 v[116:119], v[24:31], v[230:237], v[116:119], v39, v39 op_sel_hi:[0,0,0]
	v_mfma_scale_f32_16x16x128_f8f6f4 v[104:107], v[16:23], v[238:245], v[104:107], v39, v39 op_sel_hi:[0,0,0]
	v_mfma_scale_f32_16x16x128_f8f6f4 v[100:103], v[24:31], v[238:245], v[100:103], v39, v39 op_sel_hi:[0,0,0]
	s_setprio 0
	s_barrier
	s_add_u32 s0, s22, 0x8000
	s_addc_u32 s1, s23, 0
	s_mov_b32 m0, s70
	v_lshl_add_u64 v[164:165], s[0:1], 0, v[174:175]
	ds_read_b128 v[186:189], v228 offset:49152
	ds_read_b128 v[190:193], v228 offset:50176
	ds_read_b128 v[194:197], v228 offset:51200
	ds_read_b128 v[198:201], v228 offset:52224
	ds_read_b128 v[230:233], v228 offset:53248
	ds_read_b128 v[234:237], v228 offset:54272
	ds_read_b128 v[238:241], v228 offset:55296
	ds_read_b128 v[242:245], v228 offset:56320
	global_load_lds_dwordx4 v[164:165], off
	v_lshl_add_u64 v[164:165], s[0:1], 0, v[176:177]
	s_add_u32 s0, s22, 0xc000
	s_mov_b32 m0, s71
	s_addc_u32 s1, s23, 0
	global_load_lds_dwordx4 v[164:165], off
	v_lshl_add_u64 v[164:165], s[0:1], 0, v[174:175]
	s_mov_b32 m0, s93
	s_nop 0
	global_load_lds_dwordx4 v[164:165], off
	v_lshl_add_u64 v[164:165], s[0:1], 0, v[176:177]
	s_mov_b32 m0, s94
	s_nop 0
	global_load_lds_dwordx4 v[164:165], off
	v_lshl_add_u64 v[164:165], v[182:183], 0, s[24:25]
	s_mov_b32 m0, s72
	s_nop 0
	global_load_lds_dwordx4 v[164:165], off
	v_lshl_add_u64 v[164:165], v[184:185], 0, s[24:25]
	s_mov_b32 m0, s73
	s_nop 0
	global_load_lds_dwordx4 v[164:165], off
	s_waitcnt vmcnt(8)
	s_waitcnt lgkmcnt(0)
	s_barrier
	s_setprio 1
	s_waitcnt lgkmcnt(0)
	v_mfma_scale_f32_16x16x128_f8f6f4 v[96:99], v[0:7], v[186:193], v[96:99], v39, v39 op_sel_hi:[0,0,0]
	v_mfma_scale_f32_16x16x128_f8f6f4 v[92:95], v[8:15], v[186:193], v[92:95], v39, v39 op_sel_hi:[0,0,0]
	v_mfma_scale_f32_16x16x128_f8f6f4 v[80:83], v[0:7], v[194:201], v[80:83], v39, v39 op_sel_hi:[0,0,0]
	v_mfma_scale_f32_16x16x128_f8f6f4 v[76:79], v[8:15], v[194:201], v[76:79], v39, v39 op_sel_hi:[0,0,0]
	v_mfma_scale_f32_16x16x128_f8f6f4 v[64:67], v[0:7], v[230:237], v[64:67], v39, v39 op_sel_hi:[0,0,0]
	v_mfma_scale_f32_16x16x128_f8f6f4 v[60:63], v[8:15], v[230:237], v[60:63], v39, v39 op_sel_hi:[0,0,0]
	v_mfma_scale_f32_16x16x128_f8f6f4 v[48:51], v[0:7], v[238:245], v[48:51], v39, v39 op_sel_hi:[0,0,0]
	v_mfma_scale_f32_16x16x128_f8f6f4 v[44:47], v[8:15], v[238:245], v[44:47], v39, v39 op_sel_hi:[0,0,0]
	s_setprio 0
	s_setprio 1
	v_mfma_scale_f32_16x16x128_f8f6f4 v[88:91], v[16:23], v[186:193], v[88:91], v39, v39 op_sel_hi:[0,0,0]
	v_mfma_scale_f32_16x16x128_f8f6f4 v[84:87], v[24:31], v[186:193], v[84:87], v39, v39 op_sel_hi:[0,0,0]
	v_mfma_scale_f32_16x16x128_f8f6f4 v[72:75], v[16:23], v[194:201], v[72:75], v39, v39 op_sel_hi:[0,0,0]
	v_mfma_scale_f32_16x16x128_f8f6f4 v[68:71], v[24:31], v[194:201], v[68:71], v39, v39 op_sel_hi:[0,0,0]
	v_mfma_scale_f32_16x16x128_f8f6f4 v[56:59], v[16:23], v[230:237], v[56:59], v39, v39 op_sel_hi:[0,0,0]
	v_mfma_scale_f32_16x16x128_f8f6f4 v[52:55], v[24:31], v[230:237], v[52:55], v39, v39 op_sel_hi:[0,0,0]
	v_mfma_scale_f32_16x16x128_f8f6f4 v[40:43], v[16:23], v[238:245], v[40:43], v39, v39 op_sel_hi:[0,0,0]
	v_mfma_scale_f32_16x16x128_f8f6f4 v[34:37], v[24:31], v[238:245], v[34:37], v39, v39 op_sel_hi:[0,0,0]
	s_setprio 0
	s_barrier
	s_add_i32 vcc_lo, vcc_lo, 2
	s_add_u32 s51, s51, 0x10000
	s_addc_u32 s57, s57, 0
	s_add_u32 s20, s20, 0x100
	s_addc_u32 s21, s21, 0
	s_cmp_gt_u32 vcc_lo, 5
	s_cbranch_scc0 .LBB0_42
	s_and_b64 vcc, exec, s[36:37]
	s_cbranch_vccz .LBB0_45
	s_barrier
;     __device__ __forceinline__ void operator()(const f32x4 (&acc)[2][2][4][2], const Unit& u, int wr, int wc, int fr, int fq, const LAS float* lb) const {
;         const int rl0 = wr * 64 + fr, col0 = u.pn * BM + wc * 32 + 8 * fq;
;         const int nvalid = cnt[u.e] - (u.pm - mpre[u.e]) * BM;
;         const float* be = bdn + (size_t)u.e * 1024;
;         f32x4 bv[2][2];
; #pragma unroll
;         for (int bj = 0; bj < 2; ++bj)
; #pragma unroll
;             for (int n = 0; n < 2; ++n) bv[bj][n] = *(const f32x4*)(be + col0 + bj * HALF + 4 * n);
;         int slots[2][4]; float gts[2][4];
; #pragma unroll
;         for (int ai = 0; ai < 2; ++ai)
; #pragma unroll
;             for (int m = 0; m < 4; ++m) { slots[ai][m] = rowslot[u.pm * BM + rl0 + ai * HALF + m * 16]; gts[ai][m] = slotg[u.pm * BM + rl0 + ai * HALF + m * 16]; }
; #pragma unroll
;         for (int ai = 0; ai < 2; ++ai)
; #pragma unroll
;             for (int m = 0; m < 4; ++m) { const int rl = rl0 + ai * HALF + m * 16;
;                 if (rl < nvalid) { const int slot = slots[ai][m]; const float g = gts[ai][m]; bf16_t* rowp = Y + (size_t)slot * 1024 + col0;
; #pragma unroll
;                     for (int bj = 0; bj < 2; ++bj) { const f32x4 v0 = (acc[ai][bj][m][0] * (1.0f / (W8_SCALE * ACT8_SCALE)) + bv[bj][0]) * g, v1 = (acc[ai][bj][m][1] * (1.0f / (W8_SCALE * ACT8_SCALE)) + bv[bj][1]) * g;
.LBB0_45:
	s_and_b32 s98, s16, 1
	s_lshl_b32 s98, s98, 12
	s_add_i32 s99, s98, 0x20100
	v_and_b32_e32 v204, 15, v168
	v_or_b32_e32 v204, s66, v204
	v_lshl_add_u32 v204, v204, 2, s99
	v_lshrrev_b32_e32 v205, 1, v168
	v_and_b32_e32 v205, 24, v205
	v_or_b32_e32 v205, s67, v205
	s_add_i32 s99, s98, 0x20900
	v_lshl_add_u32 v205, v205, 2, s99
	s_lshl_b32 s99, s56, 2
	s_add_i32 s99, s99, s98
	s_add_i32 s99, s99, 0x20d00
	v_mov_b32_e32 v169, s99
	v_mov_b32_e32 v18, v168
	s_lshl_b32 s0, s58, 8
	v_lshrrev_b32_e32 v0, 1, v18
	s_ashr_i32 s57, s56, 31
	v_and_or_b32 v0, v0, 24, s0
	s_lshl_b64 s[0:1], s[56:57], 2
	v_readlane_b32 s20, v254, 49
	v_readlane_b32 s21, v254, 50
	s_add_u32 s0, s20, s0
	s_addc_u32 s1, s21, s1
	ds_read_b32 v27, v169
	s_lshl_b32 s0, s56, 2
	v_and_or_b32 v19, v18, 15, s66
	s_add_i32 s0, s0, 0
	v_lshl_add_u32 v20, s40, 8, v19
	s_add_i32 s12, s0, 0x20000
	s_lshl_b64 s[0:1], s[56:57], 12
	v_readlane_b32 s17, v254, 53
	v_or_b32_e32 v22, 16, v20
	v_or_b32_e32 v16, s67, v0
	s_add_u32 s0, s17, s0
	v_readlane_b32 s17, v254, 54
	v_ashrrev_i32_e32 v23, 31, v22
	v_readlane_b32 s22, v251, 25
	v_readlane_b32 s20, v251, 27
	s_addc_u32 s1, s17, s1
	v_ashrrev_i32_e32 v17, 31, v16
	v_lshlrev_b64 v[22:23], 2, v[22:23]
	v_readlane_b32 s23, v251, 26
	v_readlane_b32 s21, v251, 28
	v_lshl_add_u64 v[4:5], v[16:17], 2, s[0:1]
	v_lshl_add_u64 v[24:25], s[22:23], 0, v[22:23]
	v_lshl_add_u64 v[22:23], s[20:21], 0, v[22:23]
	ds_read_b128 v[8:11], v205 offset:16
	ds_read_b128 v[12:15], v205
	ds_read_b128 v[0:3], v205 offset:528
	s_nop 0
	ds_read_b128 v[4:7], v205 offset:512
	v_ashrrev_i32_e32 v21, 31, v20
	ds_read_b32 v194, v204 offset:64
	ds_read_b32 v192, v204 offset:1088
	v_or_b32_e32 v22, 32, v20
	v_ashrrev_i32_e32 v23, 31, v22
	v_lshlrev_b64 v[22:23], 2, v[22:23]
	v_lshl_add_u64 v[24:25], s[22:23], 0, v[22:23]
	v_lshl_add_u64 v[22:23], s[20:21], 0, v[22:23]
	ds_read_b32 v190, v204 offset:128
	ds_read_b32 v188, v204 offset:1152
	v_or_b32_e32 v22, 48, v20
	v_ashrrev_i32_e32 v23, 31, v22
	v_lshlrev_b64 v[22:23], 2, v[22:23]
	v_lshlrev_b64 v[196:197], 2, v[20:21]
	s_mov_b64 s[0:1], 0x200
	v_lshl_add_u64 v[24:25], s[22:23], 0, v[22:23]
	v_lshl_add_u64 v[22:23], s[20:21], 0, v[22:23]
	v_lshl_add_u64 v[20:21], v[196:197], 0, s[0:1]
	ds_read_b32 v186, v204 offset:192
	ds_read_b32 v184, v204 offset:1216
	v_lshl_add_u64 v[22:23], s[22:23], 0, v[20:21]
	v_lshl_add_u64 v[20:21], s[20:21], 0, v[20:21]
	s_mov_b64 s[0:1], 0x240
	ds_read_b32 v182, v204 offset:512
	ds_read_b32 v30, v204 offset:1536
	v_lshl_add_u64 v[20:21], v[196:197], 0, s[0:1]
	v_lshl_add_u64 v[22:23], s[22:23], 0, v[20:21]
	v_lshl_add_u64 v[20:21], s[20:21], 0, v[20:21]
	s_mov_b64 s[0:1], 0x280
	ds_read_b32 v28, v204 offset:576
	ds_read_b32 v26, v204 offset:1600
	v_lshl_add_u64 v[20:21], v[196:197], 0, s[0:1]
	s_mov_b64 s[0:1], 0x2c0
	v_lshl_add_u64 v[22:23], s[22:23], 0, v[20:21]
	v_lshl_add_u64 v[20:21], s[20:21], 0, v[20:21]
	v_lshl_add_u64 v[164:165], v[196:197], 0, s[0:1]
	ds_read_b32 v24, v204 offset:640
	s_nop 0
	ds_read_b32 v22, v204 offset:1664
	v_lshl_add_u64 v[20:21], s[22:23], 0, v[164:165]
	v_lshl_add_u64 v[164:165], s[20:21], 0, v[164:165]
	ds_read_b32 v20, v204 offset:704
	s_nop 0
	ds_read_b32 v18, v204 offset:1728
	v_mov_b32_e32 v21, s12
	ds_read_b32 v21, v21
	s_waitcnt lgkmcnt(0)
	v_subrev_u32_e32 v21, s40, v21
	v_lshlrev_b32_e32 v21, 8, v21
	v_readlane_b32 s0, v251, 27
	v_readlane_b32 s1, v251, 28
	s_nop 0
	v_lshl_add_u64 v[164:165], s[0:1], 0, v[196:197]
	v_lshl_add_u64 v[196:197], s[22:23], 0, v[196:197]
	ds_read_b32 v164, v204 offset:1024
	ds_read_b32 v196, v204
	s_waitcnt lgkmcnt(0)
	v_add_u32_e32 v21, v21, v27
	v_cmp_lt_i32_e32 vcc, v19, v21
	s_and_saveexec_b64 s[20:21], vcc
	s_mov_b32 s12, 0x3b000000
	s_cbranch_execz .LBB0_47
	v_readlane_b32 s0, v251, 27
	v_readlane_b32 s1, v251, 28
	v_pk_fma_f32 v[162:163], v[162:163], s[12:13], v[14:15] op_sel_hi:[1,0,1]
	v_pk_fma_f32 v[160:161], v[160:161], s[12:13], v[12:13] op_sel_hi:[1,0,1]
	v_pk_fma_f32 v[158:159], v[158:159], s[12:13], v[10:11] op_sel_hi:[1,0,1]
	v_pk_fma_f32 v[156:157], v[156:157], s[12:13], v[8:9] op_sel_hi:[1,0,1]
	v_pk_fma_f32 v[150:151], v[150:151], s[12:13], v[2:3] op_sel_hi:[1,0,1]
	v_pk_fma_f32 v[148:149], v[148:149], s[12:13], v[0:1] op_sel_hi:[1,0,1]
	v_pk_fma_f32 v[154:155], v[154:155], s[12:13], v[6:7] op_sel_hi:[1,0,1]
	v_pk_fma_f32 v[152:153], v[152:153], s[12:13], v[4:5] op_sel_hi:[1,0,1]
	v_pk_mul_f32 v[162:163], v[162:163], v[164:165] op_sel_hi:[1,0]
	v_pk_mul_f32 v[160:161], v[160:161], v[164:165] op_sel_hi:[1,0]
	v_ashrrev_i32_e32 v197, 31, v196
	v_lshlrev_b64 v[196:197], 11, v[196:197]
	v_lshl_add_u64 v[196:197], s[96:97], 0, v[196:197]
	v_lshl_add_u64 v[196:197], v[16:17], 1, v[196:197]
	v_pk_mul_f32 v[198:199], v[158:159], v[164:165] op_sel_hi:[1,0]
	v_pk_mul_f32 v[158:159], v[156:157], v[164:165] op_sel_hi:[1,0]
	v_cvt_pk_bf16_f32 v156, v160, v161
	v_cvt_pk_bf16_f32 v157, v162, v163
	v_pk_mul_f32 v[154:155], v[154:155], v[164:165] op_sel_hi:[1,0]
	v_cvt_pk_bf16_f32 v158, v158, v159
	v_cvt_pk_bf16_f32 v159, v198, v199
	global_store_dwordx4 v[196:197], v[156:159], off
	v_pk_mul_f32 v[152:153], v[152:153], v[164:165] op_sel_hi:[1,0]
	s_nop 0
	v_pk_mul_f32 v[156:157], v[150:151], v[164:165] op_sel_hi:[1,0]
	v_pk_mul_f32 v[150:151], v[148:149], v[164:165] op_sel_hi:[1,0]
	v_cvt_pk_bf16_f32 v148, v152, v153
	v_cvt_pk_bf16_f32 v149, v154, v155
	s_nop 0
	v_cvt_pk_bf16_f32 v150, v150, v151
	v_cvt_pk_bf16_f32 v151, v156, v157
	global_store_dwordx4 v[196:197], v[148:151], off offset:256
